# v33: v32 + phase_fix rewritten (4 channels per item, all operand loads issued together, branch-free)
# baseline (speedup 1.0000x reference)
.LBB0_851:
	s_or_b64 exec, exec, s[2:3]
	s_waitcnt lgkmcnt(0)
	v_mov_b32_e32 v0, v234
	v_readlane_b32 s2, v253, 8
	s_barrier
	v_add_u32_e32 v13, s2, v0
	v_readlane_b32 s50, v254, 46
	v_readlane_b32 s52, v253, 14
	v_readlane_b32 s53, v253, 15
	s_mov_b64 s[34:35], exec
	s_mov_b32 s51, 0x5d1746
	s_movk_i32 s58, 0x7f
	s_movk_i32 s59, 0x1600
.Lfx_loop:
	v_cmp_gt_u32_e32 vcc, 0x58000, v13
	s_and_b64 exec, exec, vcc
	s_cbranch_execz .LBB0_870
	v_mul_hi_u32 v14, v13, s51
	v_mul_u32_u24_e32 v15, 0x2c0, v14
	v_sub_u32_e32 v15, v13, v15
	v_lshrrev_b32_e32 v16, 1, v14
	v_and_b32_e32 v17, 1, v14
	v_lshl_add_u32 v18, v16, 2, v17
	v_lshl_add_u32 v18, v17, 1, v18
	v_mul_u32_u24_e32 v18, 0x5800, v18
	v_lshl_add_u32 v19, v15, 4, v18
	v_and_b32_e32 v26, 63, v16
	v_lshl_or_b32 v26, v17, 6, v26
	v_cmp_eq_u32_e64 s[54:55], 0, v26
	v_cmp_eq_u32_e64 s[56:57], s58, v26
	v_subrev_u32_e32 v20, 0x5800, v19
	v_add_u32_e32 v21, 0x5800, v19
	v_cndmask_b32_e64 v20, v20, v19, s[54:55]
	v_cndmask_b32_e64 v21, v21, v19, s[56:57]
	v_add_u32_e32 v22, 0x2c00, v19
	v_add_u32_e32 v23, 0x2c00, v20
	v_add_u32_e32 v24, 0x2c00, v21
	v_lshlrev_b32_e32 v25, 4, v15
	v_add_u32_e32 v28, 0x2c00, v25
	v_add_u32_e32 v29, 0x5800, v25
	v_add_u32_e32 v30, 0x8400, v25
	v_add_u32_e32 v31, 0xb000, v25
	v_add_u32_e32 v88, 0xdc00, v25
	global_load_dwordx4 v[32:35], v19, s[52:53]
	global_load_dwordx4 v[36:39], v20, s[52:53]
	global_load_dwordx4 v[40:43], v21, s[52:53]
	global_load_dwordx4 v[44:47], v22, s[52:53]
	global_load_dwordx4 v[48:51], v23, s[52:53]
	global_load_dwordx4 v[52:55], v24, s[52:53]
	global_load_dwordx4 v[56:59], v25, s[38:39]
	global_load_dwordx4 v[60:63], v29, s[38:39]
	global_load_dwordx4 v[64:67], v31, s[38:39]
	global_load_dwordx4 v[68:71], v28, s[38:39]
	global_load_dwordx4 v[72:75], v30, s[38:39]
	global_load_dwordx4 v[76:79], v88, s[38:39]
	global_load_dwordx4 v[80:83], v25, s[40:41]
	global_load_dwordx4 v[84:87], v28, s[40:41]
	v_lshlrev_b32_e32 v27, 7, v16
	v_mad_u32_u24 v27, v17, s58, v27
	v_mul_lo_u32 v27, v27, s59
	v_lshl_add_u32 v27, v15, 3, v27
	s_waitcnt vmcnt(0)
	v_cndmask_b32_e64 v36, v36, 0, s[54:55]
	v_cndmask_b32_e64 v48, v48, 0, s[54:55]
	v_cndmask_b32_e64 v40, v40, 0, s[56:57]
	v_cndmask_b32_e64 v52, v52, 0, s[56:57]
	v_cndmask_b32_e64 v37, v37, 0, s[54:55]
	v_cndmask_b32_e64 v49, v49, 0, s[54:55]
	v_cndmask_b32_e64 v41, v41, 0, s[56:57]
	v_cndmask_b32_e64 v53, v53, 0, s[56:57]
	v_cndmask_b32_e64 v38, v38, 0, s[54:55]
	v_cndmask_b32_e64 v50, v50, 0, s[54:55]
	v_cndmask_b32_e64 v42, v42, 0, s[56:57]
	v_cndmask_b32_e64 v54, v54, 0, s[56:57]
	v_cndmask_b32_e64 v39, v39, 0, s[54:55]
	v_cndmask_b32_e64 v51, v51, 0, s[54:55]
	v_cndmask_b32_e64 v43, v43, 0, s[56:57]
	v_cndmask_b32_e64 v55, v55, 0, s[56:57]
	v_mul_f32_e32 v90, v32, v60
	v_mul_f32_e32 v91, v33, v61
	v_mul_f32_e32 v92, v34, v62
	v_mul_f32_e32 v93, v35, v63
	v_fmac_f32_e32 v90, v36, v56
	v_fmac_f32_e32 v91, v37, v57
	v_fmac_f32_e32 v92, v38, v58
	v_fmac_f32_e32 v93, v39, v59
	v_fmac_f32_e32 v90, v40, v64
	v_fmac_f32_e32 v91, v41, v65
	v_fmac_f32_e32 v92, v42, v66
	v_fmac_f32_e32 v93, v43, v67
	v_add_f32_e32 v90, v80, v90
	v_add_f32_e32 v91, v81, v91
	v_add_f32_e32 v92, v82, v92
	v_add_f32_e32 v93, v83, v93
	v_mul_f32_e32 v94, v48, v68
	v_mul_f32_e32 v95, v49, v69
	v_mul_f32_e32 v96, v50, v70
	v_mul_f32_e32 v97, v51, v71
	v_mul_f32_e32 v98, v52, v76
	v_mul_f32_e32 v99, v53, v77
	v_mul_f32_e32 v100, v54, v78
	v_mul_f32_e32 v101, v55, v79
	v_fma_f32 v94, v44, v72, v94
	v_fma_f32 v95, v45, v73, v95
	v_fma_f32 v96, v46, v74, v96
	v_fma_f32 v97, v47, v75, v97
	v_add_f32_e32 v94, v94, v98
	v_add_f32_e32 v95, v95, v99
	v_add_f32_e32 v96, v96, v100
	v_add_f32_e32 v97, v97, v101
	v_add_f32_e32 v94, v84, v94
	v_add_f32_e32 v95, v85, v95
	v_add_f32_e32 v96, v86, v96
	v_add_f32_e32 v97, v87, v97
	v_mul_f32_e32 v102, 0xbfb8aa3b, v90
	v_mul_f32_e32 v103, 0xbfb8aa3b, v91
	v_mul_f32_e32 v104, 0xbfb8aa3b, v92
	v_mul_f32_e32 v105, 0xbfb8aa3b, v93
	v_exp_f32_e32 v102, v102
	v_exp_f32_e32 v103, v103
	v_exp_f32_e32 v104, v104
	v_exp_f32_e32 v105, v105
	v_add_f32_e32 v102, 1.0, v102
	v_add_f32_e32 v103, 1.0, v103
	v_add_f32_e32 v104, 1.0, v104
	v_add_f32_e32 v105, 1.0, v105
	v_rcp_f32_e32 v102, v102
	v_rcp_f32_e32 v103, v103
	v_rcp_f32_e32 v104, v104
	v_rcp_f32_e32 v105, v105
	v_mul_f32_e32 v102, v90, v102
	v_mul_f32_e32 v103, v91, v103
	v_mul_f32_e32 v104, v92, v104
	v_mul_f32_e32 v105, v93, v105
	v_mul_f32_e32 v102, v102, v94
	v_mul_f32_e32 v103, v103, v95
	v_mul_f32_e32 v104, v104, v96
	v_mul_f32_e32 v105, v105, v97
	v_cvt_pk_bf16_f32 v102, v102, v103
	v_cvt_pk_bf16_f32 v103, v104, v105
	global_store_dwordx2 v27, v[102:103], s[18:19]
	v_add_u32_e32 v13, s50, v13
	s_branch .Lfx_loop
